# grid barrier: L1 invalidate issued after the arrive atomic returns and after the XCD leader's write-back + top-level arrive
# speedup vs baseline: 1.0010x; 1.0010x over previous
.LBB0_1024:
	s_waitcnt vmcnt(0)
	s_waitcnt vmcnt(0) lgkmcnt(0)
	s_barrier
	s_and_saveexec_b64 s[6:7], s[52:53]
	s_cbranch_execz .LBB0_1078
	s_getreg_b32 s0, hwreg(HW_REG_XCC_ID, 0, 4)
	s_and_b32 s0, s0, 15
	s_lshl_b32 s2, s0, 8
	s_add_u32 s2, s2, 0x494b000
	s_add_u32 s8, s90, s2
	s_addc_u32 s9, s91, 0
	v_mov_b32_e32 v165, 1
	v_mov_b32_e32 v166, 0x1000
	global_atomic_add v165, v166, v165, s[8:9] offset:1024 sc0
	v_readlane_b32 s1, v255, 10
	v_mov_b32_e32 v0, s1
	ds_read_b32 v2, v0
	v_readlane_b32 s1, v255, 11
	s_waitcnt lgkmcnt(0)
	v_cmp_ne_u32_e32 vcc, 0, v2
	v_mov_b32_e32 v0, s1
	ds_read_b32 v0, v0
	s_cbranch_vccnz .LBB0_1042
	s_add_u32 s8, s90, 0x494b200
	s_addc_u32 s9, s91, 0
	s_add_u32 s10, s90, 0x494b400
	s_addc_u32 s11, s91, 0
	s_add_u32 s12, s90, 0x494b500
	s_addc_u32 s13, s91, 0
	s_add_u32 s16, s90, 0x494b600
	s_addc_u32 s17, s91, 0
	s_add_u32 s18, s90, 0x494b700
	s_addc_u32 s19, s91, 0
	s_add_u32 s20, s90, 0x494b800
	s_addc_u32 s21, s91, 0
	s_add_u32 s22, s90, 0x494b900
	s_addc_u32 s23, s91, 0
	s_add_u32 s24, s90, 0x494ba00
	s_addc_u32 s25, s91, 0
	s_add_u32 s28, s90, 0x494bb00
	s_addc_u32 s29, s91, 0
	s_add_u32 s36, s90, 0x494bc00
	s_addc_u32 s37, s91, 0
	s_add_u32 s58, s90, 0x494bd00
	s_addc_u32 s59, s91, 0
	s_add_u32 s62, s90, 0x494be00
	s_addc_u32 s63, s91, 0
	s_add_u32 s66, s90, 0x494bf00
	s_addc_u32 s67, s91, 0
	s_add_u32 s72, s90, 0x494c000
	s_addc_u32 s73, s91, 0
	s_add_u32 s74, s90, 0x494c100
	s_addc_u32 s75, s91, 0
	s_add_u32 s88, s90, 0x494c200
	s_addc_u32 s89, s91, 0
	s_add_u32 s92, s90, 0x494c300
	s_addc_u32 s93, s91, 0
	s_mov_b32 s4, 1
	s_branch .LBB0_1028

.LBB0_1042:
	v_cvt_f32_u32_e32 v4, v2
	v_sub_u32_e32 v3, 0, v2
	v_rcp_iflag_f32_e32 v4, v4
	s_nop 0
	v_mul_f32_e32 v4, 0x4f7ffffe, v4
	v_cvt_u32_f32_e32 v4, v4
	v_mul_lo_u32 v1, v3, v4
	v_mul_hi_u32 v1, v4, v1
	v_add_u32_e32 v1, v4, v1
	s_waitcnt vmcnt(0)
	v_mov_b32_e32 v5, v165
	v_mul_hi_u32 v1, v5, v1
	v_mul_lo_u32 v3, v1, v2
	v_sub_u32_e32 v3, v5, v3
	v_add_u32_e32 v4, 1, v1
	v_cmp_ge_u32_e32 vcc, v3, v2
	s_nop 1
	v_cndmask_b32_e32 v1, v1, v4, vcc
	v_sub_u32_e32 v4, v3, v2
	v_cndmask_b32_e32 v3, v3, v4, vcc
	v_add_u32_e32 v4, 1, v1
	v_cmp_ge_u32_e32 vcc, v3, v2
	v_add_u32_e32 v3, 1, v5
	s_nop 0
	v_cndmask_b32_e32 v1, v1, v4, vcc
	v_mul_lo_u32 v4, v2, v1
	v_add_u32_e32 v2, v4, v2
	v_cmp_ne_u32_e32 vcc, v3, v2
	s_waitcnt lgkmcnt(0)
	v_mad_u32_u24 v5, v1, v0, v0
	s_add_u32 s10, s90, 0x494e400
	s_addc_u32 s11, s91, 0
	s_cbranch_vccnz .Lgb_inv
	buffer_wbl2 sc1
	s_waitcnt vmcnt(0)
	v_mov_b32_e32 v2, 1
	global_atomic_add v159, v2, s[10:11]
.Lgb_inv:
	buffer_inv sc1
.Lgb_poll:
	global_load_dword v0, v159, s[10:11] sc1
	s_waitcnt vmcnt(0)
	v_cmp_lt_u32_e32 vcc, v0, v5
	s_cbranch_vccz .Lgb_done
	s_sleep 1
	s_branch .Lgb_poll
